# scan consumer: scalar f32 ops + paired partial writes (ds_write2st64); finalize rewrite kept
# speedup vs baseline: 1.0031x; 1.0031x over previous
; __device__ __forceinline__ float allreduce16(float x) { x += dppf(x, 0); x += dppf(x, 1); x += dppf(x, 2); x += dppf(x, 3); return x; }
; __device__ void rw_scan(const Params& p, int l, unsigned char* shm, int item) {
;     ...
;         for (int ck = 0; ck < T / TC; ++ck) {
;             const float* sr = (const float*)(shm + (ck & 1) * RWB) + ks; const float* sv = (const float*)(shm + (ck & 1) * RWB) + 5 * 2048 + rowl;
;             f32x4 a4 = *(const f32x4*)(sr + 3 * 2048), w4 = *(const f32x4*)(sr + 2048), b4 = *(const f32x4*)(sr + 4 * 2048), k4 = *(const f32x4*)(sr + 2 * 2048), r4 = *(const f32x4*)sr;
;             float vv = sv[0];
; #pragma unroll
;             for (int hs = 0; hs < 2; ++hs) {
; #pragma unroll
;                 for (int s2 = 0; s2 < 16; ++s2) {
;                     const int s = hs * 16 + s2, sn = (s + 1) & (TC - 1);
;                     const f32x4 na4 = *(const f32x4*)(sr + 3 * 2048 + sn * 64), nw4 = *(const f32x4*)(sr + 2048 + sn * 64), nb4 = *(const f32x4*)(sr + 4 * 2048 + sn * 64), nk4 = *(const f32x4*)(sr + 2 * 2048 + sn * 64), nr4 = *(const f32x4*)(sr + sn * 64);
;                     const float nvv = sv[sn * 16];
;                     f32x2 tq = S01 * (f32x2){a4[0], a4[1]}; tq = S23 * (f32x2){a4[2], a4[3]} + tq;
;                     const float sav = allreduce16(tq[0] + tq[1]);
;                     f32x2 u0 = (f32x2){b4[0], b4[1]} * sav, u1 = (f32x2){b4[2], b4[3]} * sav;
;                     u0 = (f32x2){k4[0], k4[1]} * vv + u0; u1 = (f32x2){k4[2], k4[3]} * vv + u1;
;                     S01 = S01 * (f32x2){w4[0], w4[1]} + u0; S23 = S23 * (f32x2){w4[2], w4[3]} + u1;
;                     f32x2 oq = S01 * (f32x2){r4[0], r4[1]}; oq = S23 * (f32x2){r4[2], r4[3]} + oq;
;                     pp[s2 * 64] = oq[0] + oq[1];
;                     a4 = na4; w4 = nw4; b4 = nb4; k4 = nk4; r4 = nr4; vv = nvv;
;                 }
.LBB0_304:
	s_bitcmp1_b32 s3, 0
	s_cselect_b32 s5, 0xa800, 0
	v_add_u32_e32 v35, s5, v31
	v_lshlrev_b32_e32 v0, 2, v22
	v_add3_u32 v36, s5, v0, v33
	v_add_u32_e32 v37, 0xa000, v36
	v_add_u32_e32 v38, 0xa400, v36
	ds_read_b128 v[40:43], v35 offset:24576
	ds_read_b128 v[56:59], v35 offset:8192
	ds_read_b128 v[72:75], v35 offset:32768
	ds_read_b128 v[88:91], v35 offset:16384
	ds_read_b128 v[104:107], v35 offset:0
	ds_read2_b32 v[120:121], v37 offset0:0 offset1:16
	ds_read_b128 v[44:47], v35 offset:24832
	ds_read_b128 v[60:63], v35 offset:8448
	ds_read_b128 v[76:79], v35 offset:33024
	ds_read_b128 v[92:95], v35 offset:16640
	ds_read_b128 v[108:111], v35 offset:256
	s_waitcnt lgkmcnt(5)
	v_mul_f32_e32 v10, v2, v40
	v_mul_f32_e32 v6, v88, v120
	v_fmac_f32_e32 v10, v3, v41
	v_mul_f32_e32 v7, v89, v120
	v_fmac_f32_e32 v10, v4, v42
	v_mul_f32_e32 v8, v90, v120
	v_fmac_f32_e32 v10, v5, v43
	v_mul_f32_e32 v9, v91, v120
	v_fmac_f32_e32 v6, v2, v56
	v_add_f32_dpp v10, v10, v10 quad_perm:[1,0,3,2] row_mask:0xf bank_mask:0xf bound_ctrl:1
	v_fmac_f32_e32 v7, v3, v57
	v_fmac_f32_e32 v8, v4, v58
	v_add_f32_dpp v10, v10, v10 quad_perm:[2,3,0,1] row_mask:0xf bank_mask:0xf bound_ctrl:1
	v_fmac_f32_e32 v9, v5, v59
	s_nop 0
	v_add_f32_dpp v10, v10, v10 row_half_mirror row_mask:0xf bank_mask:0xf bound_ctrl:1
	s_nop 0
	s_nop 0
	v_add_f32_dpp v10, v10, v10 row_mirror row_mask:0xf bank_mask:0xf bound_ctrl:1
	v_fmac_f32_e32 v6, v72, v10
	v_fmac_f32_e32 v7, v73, v10
	v_fmac_f32_e32 v8, v74, v10
	v_fmac_f32_e32 v9, v75, v10
	ds_read_b128 v[48:51], v35 offset:25088
	ds_read_b128 v[64:67], v35 offset:8704
	ds_read_b128 v[80:83], v35 offset:33280
	ds_read_b128 v[96:99], v35 offset:16896
	ds_read_b128 v[112:115], v35 offset:512
	ds_read2_b32 v[122:123], v37 offset0:32 offset1:48
	s_waitcnt lgkmcnt(6)
	v_mul_f32_e32 v11, v6, v44
	v_mul_f32_e32 v2, v92, v121
	v_fmac_f32_e32 v11, v7, v45
	v_mul_f32_e32 v3, v93, v121
	v_fmac_f32_e32 v11, v8, v46
	v_mul_f32_e32 v4, v94, v121
	v_fmac_f32_e32 v11, v9, v47
	v_mul_f32_e32 v5, v95, v121
	v_fmac_f32_e32 v2, v6, v60
	v_add_f32_dpp v11, v11, v11 quad_perm:[1,0,3,2] row_mask:0xf bank_mask:0xf bound_ctrl:1
	v_fmac_f32_e32 v3, v7, v61
	v_fmac_f32_e32 v4, v8, v62
	v_add_f32_dpp v11, v11, v11 quad_perm:[2,3,0,1] row_mask:0xf bank_mask:0xf bound_ctrl:1
	v_fmac_f32_e32 v5, v9, v63
	v_mul_f32_e32 v12, v6, v104
	v_add_f32_dpp v11, v11, v11 row_half_mirror row_mask:0xf bank_mask:0xf bound_ctrl:1
	v_fmac_f32_e32 v12, v7, v105
	v_fmac_f32_e32 v12, v8, v106
	v_add_f32_dpp v11, v11, v11 row_mirror row_mask:0xf bank_mask:0xf bound_ctrl:1
	v_fmac_f32_e32 v2, v76, v11
	v_fmac_f32_e32 v3, v77, v11
	v_fmac_f32_e32 v4, v78, v11
	v_fmac_f32_e32 v5, v79, v11
	v_fmac_f32_e32 v12, v9, v107
	ds_read_b128 v[52:55], v35 offset:25344
	ds_read_b128 v[68:71], v35 offset:8960
	ds_read_b128 v[84:87], v35 offset:33536
	ds_read_b128 v[100:103], v35 offset:17152
	ds_read_b128 v[116:119], v35 offset:768
	s_waitcnt lgkmcnt(5)
	v_mul_f32_e32 v10, v2, v48
	v_mul_f32_e32 v6, v96, v122
	v_fmac_f32_e32 v10, v3, v49
	v_mul_f32_e32 v7, v97, v122
	v_fmac_f32_e32 v10, v4, v50
	v_mul_f32_e32 v8, v98, v122
	v_fmac_f32_e32 v10, v5, v51
	v_mul_f32_e32 v9, v99, v122
	v_fmac_f32_e32 v6, v2, v64
	v_add_f32_dpp v10, v10, v10 quad_perm:[1,0,3,2] row_mask:0xf bank_mask:0xf bound_ctrl:1
	v_fmac_f32_e32 v7, v3, v65
	v_fmac_f32_e32 v8, v4, v66
	v_add_f32_dpp v10, v10, v10 quad_perm:[2,3,0,1] row_mask:0xf bank_mask:0xf bound_ctrl:1
	v_fmac_f32_e32 v9, v5, v67
	v_mul_f32_e32 v13, v2, v108
	v_add_f32_dpp v10, v10, v10 row_half_mirror row_mask:0xf bank_mask:0xf bound_ctrl:1
	v_fmac_f32_e32 v13, v3, v109
	v_fmac_f32_e32 v13, v4, v110
	v_add_f32_dpp v10, v10, v10 row_mirror row_mask:0xf bank_mask:0xf bound_ctrl:1
	v_fmac_f32_e32 v6, v80, v10
	v_fmac_f32_e32 v7, v81, v10
	v_fmac_f32_e32 v8, v82, v10
	v_fmac_f32_e32 v9, v83, v10
	v_fmac_f32_e32 v13, v5, v111
	ds_write2st64_b32 v30, v12, v13 offset0:0 offset1:1
	ds_read_b128 v[40:43], v35 offset:25600
	ds_read_b128 v[56:59], v35 offset:9216
	ds_read_b128 v[72:75], v35 offset:33792
	ds_read_b128 v[88:91], v35 offset:17408
	ds_read_b128 v[104:107], v35 offset:1024
	ds_read2_b32 v[124:125], v37 offset0:64 offset1:80
	s_waitcnt lgkmcnt(7)
	v_mul_f32_e32 v11, v6, v52
	v_mul_f32_e32 v2, v100, v123
	v_fmac_f32_e32 v11, v7, v53
	v_mul_f32_e32 v3, v101, v123
	v_fmac_f32_e32 v11, v8, v54
	v_mul_f32_e32 v4, v102, v123
	v_fmac_f32_e32 v11, v9, v55
	v_mul_f32_e32 v5, v103, v123
	v_fmac_f32_e32 v2, v6, v68
	v_add_f32_dpp v11, v11, v11 quad_perm:[1,0,3,2] row_mask:0xf bank_mask:0xf bound_ctrl:1
	v_fmac_f32_e32 v3, v7, v69
	v_fmac_f32_e32 v4, v8, v70
	v_add_f32_dpp v11, v11, v11 quad_perm:[2,3,0,1] row_mask:0xf bank_mask:0xf bound_ctrl:1
	v_fmac_f32_e32 v5, v9, v71
	v_mul_f32_e32 v12, v6, v112
	v_add_f32_dpp v11, v11, v11 row_half_mirror row_mask:0xf bank_mask:0xf bound_ctrl:1
	v_fmac_f32_e32 v12, v7, v113
	v_fmac_f32_e32 v12, v8, v114
	v_add_f32_dpp v11, v11, v11 row_mirror row_mask:0xf bank_mask:0xf bound_ctrl:1
	v_fmac_f32_e32 v2, v84, v11
	v_fmac_f32_e32 v3, v85, v11
	v_fmac_f32_e32 v4, v86, v11
	v_fmac_f32_e32 v5, v87, v11
	v_fmac_f32_e32 v12, v9, v115
	ds_read_b128 v[44:47], v35 offset:25856
	ds_read_b128 v[60:63], v35 offset:9472
	ds_read_b128 v[76:79], v35 offset:34048
	ds_read_b128 v[92:95], v35 offset:17664
	ds_read_b128 v[108:111], v35 offset:1280
	s_waitcnt lgkmcnt(5)
; __device__ __forceinline__ float allreduce16(float x) { x += dppf(x, 0); x += dppf(x, 1); x += dppf(x, 2); x += dppf(x, 3); return x; }
; __device__ void rw_scan(const Params& p, int l, unsigned char* shm, int item) {
;     ...
;                 for (int s2 = 0; s2 < 16; ++s2) {
;                     const int s = hs * 16 + s2, sn = (s + 1) & (TC - 1);
;                     const f32x4 na4 = *(const f32x4*)(sr + 3 * 2048 + sn * 64), nw4 = *(const f32x4*)(sr + 2048 + sn * 64), nb4 = *(const f32x4*)(sr + 4 * 2048 + sn * 64), nk4 = *(const f32x4*)(sr + 2 * 2048 + sn * 64), nr4 = *(const f32x4*)(sr + sn * 64);
;                     const float nvv = sv[sn * 16];
;                     f32x2 tq = S01 * (f32x2){a4[0], a4[1]}; tq = S23 * (f32x2){a4[2], a4[3]} + tq;
;                     const float sav = allreduce16(tq[0] + tq[1]);
;                     f32x2 u0 = (f32x2){b4[0], b4[1]} * sav, u1 = (f32x2){b4[2], b4[3]} * sav;
;                     u0 = (f32x2){k4[0], k4[1]} * vv + u0; u1 = (f32x2){k4[2], k4[3]} * vv + u1;
;                     S01 = S01 * (f32x2){w4[0], w4[1]} + u0; S23 = S23 * (f32x2){w4[2], w4[3]} + u1;
;                     f32x2 oq = S01 * (f32x2){r4[0], r4[1]}; oq = S23 * (f32x2){r4[2], r4[3]} + oq;
;                     pp[s2 * 64] = oq[0] + oq[1];
;                     a4 = na4; w4 = nw4; b4 = nb4; k4 = nk4; r4 = nr4; vv = nvv;
;                 }
	v_mul_f32_e32 v10, v2, v40
	v_mul_f32_e32 v6, v88, v124
	v_fmac_f32_e32 v10, v3, v41
	v_mul_f32_e32 v7, v89, v124
	v_fmac_f32_e32 v10, v4, v42
	v_mul_f32_e32 v8, v90, v124
	v_fmac_f32_e32 v10, v5, v43
	v_mul_f32_e32 v9, v91, v124
	v_fmac_f32_e32 v6, v2, v56
	v_add_f32_dpp v10, v10, v10 quad_perm:[1,0,3,2] row_mask:0xf bank_mask:0xf bound_ctrl:1
	v_fmac_f32_e32 v7, v3, v57
	v_fmac_f32_e32 v8, v4, v58
	v_add_f32_dpp v10, v10, v10 quad_perm:[2,3,0,1] row_mask:0xf bank_mask:0xf bound_ctrl:1
	v_fmac_f32_e32 v9, v5, v59
	v_mul_f32_e32 v13, v2, v116
	v_add_f32_dpp v10, v10, v10 row_half_mirror row_mask:0xf bank_mask:0xf bound_ctrl:1
	v_fmac_f32_e32 v13, v3, v117
	v_fmac_f32_e32 v13, v4, v118
	v_add_f32_dpp v10, v10, v10 row_mirror row_mask:0xf bank_mask:0xf bound_ctrl:1
	v_fmac_f32_e32 v6, v72, v10
	v_fmac_f32_e32 v7, v73, v10
	v_fmac_f32_e32 v8, v74, v10
	v_fmac_f32_e32 v9, v75, v10
	v_fmac_f32_e32 v13, v5, v119
	ds_write2st64_b32 v30, v12, v13 offset0:2 offset1:3
	ds_read_b128 v[48:51], v35 offset:26112
	ds_read_b128 v[64:67], v35 offset:9728
	ds_read_b128 v[80:83], v35 offset:34304
	ds_read_b128 v[96:99], v35 offset:17920
	ds_read_b128 v[112:115], v35 offset:1536
	ds_read2_b32 v[120:121], v37 offset0:96 offset1:112
	s_waitcnt lgkmcnt(7)
	v_mul_f32_e32 v11, v6, v44
	v_mul_f32_e32 v2, v92, v125
	v_fmac_f32_e32 v11, v7, v45
	v_mul_f32_e32 v3, v93, v125
	v_fmac_f32_e32 v11, v8, v46
	v_mul_f32_e32 v4, v94, v125
	v_fmac_f32_e32 v11, v9, v47
	v_mul_f32_e32 v5, v95, v125
	v_fmac_f32_e32 v2, v6, v60
	v_add_f32_dpp v11, v11, v11 quad_perm:[1,0,3,2] row_mask:0xf bank_mask:0xf bound_ctrl:1
	v_fmac_f32_e32 v3, v7, v61
	v_fmac_f32_e32 v4, v8, v62
	v_add_f32_dpp v11, v11, v11 quad_perm:[2,3,0,1] row_mask:0xf bank_mask:0xf bound_ctrl:1
	v_fmac_f32_e32 v5, v9, v63
	v_mul_f32_e32 v12, v6, v104
	v_add_f32_dpp v11, v11, v11 row_half_mirror row_mask:0xf bank_mask:0xf bound_ctrl:1
	v_fmac_f32_e32 v12, v7, v105
	v_fmac_f32_e32 v12, v8, v106
	v_add_f32_dpp v11, v11, v11 row_mirror row_mask:0xf bank_mask:0xf bound_ctrl:1
	v_fmac_f32_e32 v2, v76, v11
	v_fmac_f32_e32 v3, v77, v11
	v_fmac_f32_e32 v4, v78, v11
	v_fmac_f32_e32 v5, v79, v11
	v_fmac_f32_e32 v12, v9, v107
	ds_read_b128 v[52:55], v35 offset:26368
	ds_read_b128 v[68:71], v35 offset:9984
	ds_read_b128 v[84:87], v35 offset:34560
	ds_read_b128 v[100:103], v35 offset:18176
	ds_read_b128 v[116:119], v35 offset:1792
	s_waitcnt lgkmcnt(5)
	v_mul_f32_e32 v10, v2, v48
	v_mul_f32_e32 v6, v96, v120
	v_fmac_f32_e32 v10, v3, v49
	v_mul_f32_e32 v7, v97, v120
	v_fmac_f32_e32 v10, v4, v50
	v_mul_f32_e32 v8, v98, v120
	v_fmac_f32_e32 v10, v5, v51
	v_mul_f32_e32 v9, v99, v120
	v_fmac_f32_e32 v6, v2, v64
	v_add_f32_dpp v10, v10, v10 quad_perm:[1,0,3,2] row_mask:0xf bank_mask:0xf bound_ctrl:1
	v_fmac_f32_e32 v7, v3, v65
	v_fmac_f32_e32 v8, v4, v66
	v_add_f32_dpp v10, v10, v10 quad_perm:[2,3,0,1] row_mask:0xf bank_mask:0xf bound_ctrl:1
	v_fmac_f32_e32 v9, v5, v67
	v_mul_f32_e32 v13, v2, v108
	v_add_f32_dpp v10, v10, v10 row_half_mirror row_mask:0xf bank_mask:0xf bound_ctrl:1
	v_fmac_f32_e32 v13, v3, v109
	v_fmac_f32_e32 v13, v4, v110
	v_add_f32_dpp v10, v10, v10 row_mirror row_mask:0xf bank_mask:0xf bound_ctrl:1
	v_fmac_f32_e32 v6, v80, v10
	v_fmac_f32_e32 v7, v81, v10
	v_fmac_f32_e32 v8, v82, v10
	v_fmac_f32_e32 v9, v83, v10
	v_fmac_f32_e32 v13, v5, v111
	ds_write2st64_b32 v30, v12, v13 offset0:4 offset1:5
	ds_read_b128 v[40:43], v35 offset:26624
	ds_read_b128 v[56:59], v35 offset:10240
	ds_read_b128 v[72:75], v35 offset:34816
	ds_read_b128 v[88:91], v35 offset:18432
	ds_read_b128 v[104:107], v35 offset:2048
	ds_read2_b32 v[122:123], v37 offset0:128 offset1:144
	s_waitcnt lgkmcnt(7)
	v_mul_f32_e32 v11, v6, v52
	v_mul_f32_e32 v2, v100, v121
	v_fmac_f32_e32 v11, v7, v53
	v_mul_f32_e32 v3, v101, v121
	v_fmac_f32_e32 v11, v8, v54
	v_mul_f32_e32 v4, v102, v121
	v_fmac_f32_e32 v11, v9, v55
	v_mul_f32_e32 v5, v103, v121
	v_fmac_f32_e32 v2, v6, v68
	v_add_f32_dpp v11, v11, v11 quad_perm:[1,0,3,2] row_mask:0xf bank_mask:0xf bound_ctrl:1
	v_fmac_f32_e32 v3, v7, v69
	v_fmac_f32_e32 v4, v8, v70
	v_add_f32_dpp v11, v11, v11 quad_perm:[2,3,0,1] row_mask:0xf bank_mask:0xf bound_ctrl:1
	v_fmac_f32_e32 v5, v9, v71
	v_mul_f32_e32 v12, v6, v112
	v_add_f32_dpp v11, v11, v11 row_half_mirror row_mask:0xf bank_mask:0xf bound_ctrl:1
	v_fmac_f32_e32 v12, v7, v113
	v_fmac_f32_e32 v12, v8, v114
	v_add_f32_dpp v11, v11, v11 row_mirror row_mask:0xf bank_mask:0xf bound_ctrl:1
	v_fmac_f32_e32 v2, v84, v11
	v_fmac_f32_e32 v3, v85, v11
	v_fmac_f32_e32 v4, v86, v11
	v_fmac_f32_e32 v5, v87, v11
	v_fmac_f32_e32 v12, v9, v115
	ds_read_b128 v[44:47], v35 offset:26880
	ds_read_b128 v[60:63], v35 offset:10496
	ds_read_b128 v[76:79], v35 offset:35072
	ds_read_b128 v[92:95], v35 offset:18688
	ds_read_b128 v[108:111], v35 offset:2304
	s_waitcnt lgkmcnt(5)
	v_mul_f32_e32 v10, v2, v40
	v_mul_f32_e32 v6, v88, v122
	v_fmac_f32_e32 v10, v3, v41
	v_mul_f32_e32 v7, v89, v122
	v_fmac_f32_e32 v10, v4, v42
	v_mul_f32_e32 v8, v90, v122
	v_fmac_f32_e32 v10, v5, v43
	v_mul_f32_e32 v9, v91, v122
	v_fmac_f32_e32 v6, v2, v56
	v_add_f32_dpp v10, v10, v10 quad_perm:[1,0,3,2] row_mask:0xf bank_mask:0xf bound_ctrl:1
	v_fmac_f32_e32 v7, v3, v57
	v_fmac_f32_e32 v8, v4, v58
	v_add_f32_dpp v10, v10, v10 quad_perm:[2,3,0,1] row_mask:0xf bank_mask:0xf bound_ctrl:1
	v_fmac_f32_e32 v9, v5, v59
	v_mul_f32_e32 v13, v2, v116
	v_add_f32_dpp v10, v10, v10 row_half_mirror row_mask:0xf bank_mask:0xf bound_ctrl:1
	v_fmac_f32_e32 v13, v3, v117
	v_fmac_f32_e32 v13, v4, v118
	v_add_f32_dpp v10, v10, v10 row_mirror row_mask:0xf bank_mask:0xf bound_ctrl:1
	v_fmac_f32_e32 v6, v72, v10
	v_fmac_f32_e32 v7, v73, v10
	v_fmac_f32_e32 v8, v74, v10
	v_fmac_f32_e32 v9, v75, v10
	v_fmac_f32_e32 v13, v5, v119
	ds_write2st64_b32 v30, v12, v13 offset0:6 offset1:7
	ds_read_b128 v[48:51], v35 offset:27136
	ds_read_b128 v[64:67], v35 offset:10752
	ds_read_b128 v[80:83], v35 offset:35328
	ds_read_b128 v[96:99], v35 offset:18944
	ds_read_b128 v[112:115], v35 offset:2560
	ds_read2_b32 v[124:125], v37 offset0:160 offset1:176
	s_waitcnt lgkmcnt(7)
; __device__ __forceinline__ float allreduce16(float x) { x += dppf(x, 0); x += dppf(x, 1); x += dppf(x, 2); x += dppf(x, 3); return x; }
; __device__ void rw_scan(const Params& p, int l, unsigned char* shm, int item) {
;     ...
;                 for (int s2 = 0; s2 < 16; ++s2) {
;                     const int s = hs * 16 + s2, sn = (s + 1) & (TC - 1);
;                     const f32x4 na4 = *(const f32x4*)(sr + 3 * 2048 + sn * 64), nw4 = *(const f32x4*)(sr + 2048 + sn * 64), nb4 = *(const f32x4*)(sr + 4 * 2048 + sn * 64), nk4 = *(const f32x4*)(sr + 2 * 2048 + sn * 64), nr4 = *(const f32x4*)(sr + sn * 64);
;                     const float nvv = sv[sn * 16];
;                     f32x2 tq = S01 * (f32x2){a4[0], a4[1]}; tq = S23 * (f32x2){a4[2], a4[3]} + tq;
;                     const float sav = allreduce16(tq[0] + tq[1]);
;                     f32x2 u0 = (f32x2){b4[0], b4[1]} * sav, u1 = (f32x2){b4[2], b4[3]} * sav;
;                     u0 = (f32x2){k4[0], k4[1]} * vv + u0; u1 = (f32x2){k4[2], k4[3]} * vv + u1;
;                     S01 = S01 * (f32x2){w4[0], w4[1]} + u0; S23 = S23 * (f32x2){w4[2], w4[3]} + u1;
;                     f32x2 oq = S01 * (f32x2){r4[0], r4[1]}; oq = S23 * (f32x2){r4[2], r4[3]} + oq;
;                     pp[s2 * 64] = oq[0] + oq[1];
;                     a4 = na4; w4 = nw4; b4 = nb4; k4 = nk4; r4 = nr4; vv = nvv;
;                 }
	v_mul_f32_e32 v11, v6, v44
	v_mul_f32_e32 v2, v92, v123
	v_fmac_f32_e32 v11, v7, v45
	v_mul_f32_e32 v3, v93, v123
	v_fmac_f32_e32 v11, v8, v46
	v_mul_f32_e32 v4, v94, v123
	v_fmac_f32_e32 v11, v9, v47
	v_mul_f32_e32 v5, v95, v123
	v_fmac_f32_e32 v2, v6, v60
	v_add_f32_dpp v11, v11, v11 quad_perm:[1,0,3,2] row_mask:0xf bank_mask:0xf bound_ctrl:1
	v_fmac_f32_e32 v3, v7, v61
	v_fmac_f32_e32 v4, v8, v62
	v_add_f32_dpp v11, v11, v11 quad_perm:[2,3,0,1] row_mask:0xf bank_mask:0xf bound_ctrl:1
	v_fmac_f32_e32 v5, v9, v63
	v_mul_f32_e32 v12, v6, v104
	v_add_f32_dpp v11, v11, v11 row_half_mirror row_mask:0xf bank_mask:0xf bound_ctrl:1
	v_fmac_f32_e32 v12, v7, v105
	v_fmac_f32_e32 v12, v8, v106
	v_add_f32_dpp v11, v11, v11 row_mirror row_mask:0xf bank_mask:0xf bound_ctrl:1
	v_fmac_f32_e32 v2, v76, v11
	v_fmac_f32_e32 v3, v77, v11
	v_fmac_f32_e32 v4, v78, v11
	v_fmac_f32_e32 v5, v79, v11
	v_fmac_f32_e32 v12, v9, v107
	ds_read_b128 v[52:55], v35 offset:27392
	ds_read_b128 v[68:71], v35 offset:11008
	ds_read_b128 v[84:87], v35 offset:35584
	ds_read_b128 v[100:103], v35 offset:19200
	ds_read_b128 v[116:119], v35 offset:2816
	s_waitcnt lgkmcnt(5)
	v_mul_f32_e32 v10, v2, v48
	v_mul_f32_e32 v6, v96, v124
	v_fmac_f32_e32 v10, v3, v49
	v_mul_f32_e32 v7, v97, v124
	v_fmac_f32_e32 v10, v4, v50
	v_mul_f32_e32 v8, v98, v124
	v_fmac_f32_e32 v10, v5, v51
	v_mul_f32_e32 v9, v99, v124
	v_fmac_f32_e32 v6, v2, v64
	v_add_f32_dpp v10, v10, v10 quad_perm:[1,0,3,2] row_mask:0xf bank_mask:0xf bound_ctrl:1
	v_fmac_f32_e32 v7, v3, v65
	v_fmac_f32_e32 v8, v4, v66
	v_add_f32_dpp v10, v10, v10 quad_perm:[2,3,0,1] row_mask:0xf bank_mask:0xf bound_ctrl:1
	v_fmac_f32_e32 v9, v5, v67
	v_mul_f32_e32 v13, v2, v108
	v_add_f32_dpp v10, v10, v10 row_half_mirror row_mask:0xf bank_mask:0xf bound_ctrl:1
	v_fmac_f32_e32 v13, v3, v109
	v_fmac_f32_e32 v13, v4, v110
	v_add_f32_dpp v10, v10, v10 row_mirror row_mask:0xf bank_mask:0xf bound_ctrl:1
	v_fmac_f32_e32 v6, v80, v10
	v_fmac_f32_e32 v7, v81, v10
	v_fmac_f32_e32 v8, v82, v10
	v_fmac_f32_e32 v9, v83, v10
	v_fmac_f32_e32 v13, v5, v111
	ds_write2st64_b32 v30, v12, v13 offset0:8 offset1:9
	ds_read_b128 v[40:43], v35 offset:27648
	ds_read_b128 v[56:59], v35 offset:11264
	ds_read_b128 v[72:75], v35 offset:35840
	ds_read_b128 v[88:91], v35 offset:19456
	ds_read_b128 v[104:107], v35 offset:3072
	ds_read2_b32 v[120:121], v37 offset0:192 offset1:208
	s_waitcnt lgkmcnt(7)
	v_mul_f32_e32 v11, v6, v52
	v_mul_f32_e32 v2, v100, v125
	v_fmac_f32_e32 v11, v7, v53
	v_mul_f32_e32 v3, v101, v125
	v_fmac_f32_e32 v11, v8, v54
	v_mul_f32_e32 v4, v102, v125
	v_fmac_f32_e32 v11, v9, v55
	v_mul_f32_e32 v5, v103, v125
	v_fmac_f32_e32 v2, v6, v68
	v_add_f32_dpp v11, v11, v11 quad_perm:[1,0,3,2] row_mask:0xf bank_mask:0xf bound_ctrl:1
	v_fmac_f32_e32 v3, v7, v69
	v_fmac_f32_e32 v4, v8, v70
	v_add_f32_dpp v11, v11, v11 quad_perm:[2,3,0,1] row_mask:0xf bank_mask:0xf bound_ctrl:1
	v_fmac_f32_e32 v5, v9, v71
	v_mul_f32_e32 v12, v6, v112
	v_add_f32_dpp v11, v11, v11 row_half_mirror row_mask:0xf bank_mask:0xf bound_ctrl:1
	v_fmac_f32_e32 v12, v7, v113
	v_fmac_f32_e32 v12, v8, v114
	v_add_f32_dpp v11, v11, v11 row_mirror row_mask:0xf bank_mask:0xf bound_ctrl:1
	v_fmac_f32_e32 v2, v84, v11
	v_fmac_f32_e32 v3, v85, v11
	v_fmac_f32_e32 v4, v86, v11
	v_fmac_f32_e32 v5, v87, v11
	v_fmac_f32_e32 v12, v9, v115
	ds_read_b128 v[44:47], v35 offset:27904
	ds_read_b128 v[60:63], v35 offset:11520
	ds_read_b128 v[76:79], v35 offset:36096
	ds_read_b128 v[92:95], v35 offset:19712
	ds_read_b128 v[108:111], v35 offset:3328
	s_waitcnt lgkmcnt(5)
	v_mul_f32_e32 v10, v2, v40
	v_mul_f32_e32 v6, v88, v120
	v_fmac_f32_e32 v10, v3, v41
	v_mul_f32_e32 v7, v89, v120
	v_fmac_f32_e32 v10, v4, v42
	v_mul_f32_e32 v8, v90, v120
	v_fmac_f32_e32 v10, v5, v43
	v_mul_f32_e32 v9, v91, v120
	v_fmac_f32_e32 v6, v2, v56
	v_add_f32_dpp v10, v10, v10 quad_perm:[1,0,3,2] row_mask:0xf bank_mask:0xf bound_ctrl:1
	v_fmac_f32_e32 v7, v3, v57
	v_fmac_f32_e32 v8, v4, v58
	v_add_f32_dpp v10, v10, v10 quad_perm:[2,3,0,1] row_mask:0xf bank_mask:0xf bound_ctrl:1
	v_fmac_f32_e32 v9, v5, v59
	v_mul_f32_e32 v13, v2, v116
	v_add_f32_dpp v10, v10, v10 row_half_mirror row_mask:0xf bank_mask:0xf bound_ctrl:1
	v_fmac_f32_e32 v13, v3, v117
	v_fmac_f32_e32 v13, v4, v118
	v_add_f32_dpp v10, v10, v10 row_mirror row_mask:0xf bank_mask:0xf bound_ctrl:1
	v_fmac_f32_e32 v6, v72, v10
	v_fmac_f32_e32 v7, v73, v10
	v_fmac_f32_e32 v8, v74, v10
	v_fmac_f32_e32 v9, v75, v10
	v_fmac_f32_e32 v13, v5, v119
	ds_write2st64_b32 v30, v12, v13 offset0:10 offset1:11
	ds_read_b128 v[48:51], v35 offset:28160
	ds_read_b128 v[64:67], v35 offset:11776
	ds_read_b128 v[80:83], v35 offset:36352
	ds_read_b128 v[96:99], v35 offset:19968
	ds_read_b128 v[112:115], v35 offset:3584
	ds_read2_b32 v[122:123], v37 offset0:224 offset1:240
	s_waitcnt lgkmcnt(7)
	v_mul_f32_e32 v11, v6, v44
	v_mul_f32_e32 v2, v92, v121
	v_fmac_f32_e32 v11, v7, v45
	v_mul_f32_e32 v3, v93, v121
	v_fmac_f32_e32 v11, v8, v46
	v_mul_f32_e32 v4, v94, v121
	v_fmac_f32_e32 v11, v9, v47
	v_mul_f32_e32 v5, v95, v121
	v_fmac_f32_e32 v2, v6, v60
	v_add_f32_dpp v11, v11, v11 quad_perm:[1,0,3,2] row_mask:0xf bank_mask:0xf bound_ctrl:1
	v_fmac_f32_e32 v3, v7, v61
	v_fmac_f32_e32 v4, v8, v62
	v_add_f32_dpp v11, v11, v11 quad_perm:[2,3,0,1] row_mask:0xf bank_mask:0xf bound_ctrl:1
	v_fmac_f32_e32 v5, v9, v63
	v_mul_f32_e32 v12, v6, v104
	v_add_f32_dpp v11, v11, v11 row_half_mirror row_mask:0xf bank_mask:0xf bound_ctrl:1
	v_fmac_f32_e32 v12, v7, v105
	v_fmac_f32_e32 v12, v8, v106
	v_add_f32_dpp v11, v11, v11 row_mirror row_mask:0xf bank_mask:0xf bound_ctrl:1
	v_fmac_f32_e32 v2, v76, v11
	v_fmac_f32_e32 v3, v77, v11
	v_fmac_f32_e32 v4, v78, v11
	v_fmac_f32_e32 v5, v79, v11
	v_fmac_f32_e32 v12, v9, v107
	ds_read_b128 v[52:55], v35 offset:28416
	ds_read_b128 v[68:71], v35 offset:12032
	ds_read_b128 v[84:87], v35 offset:36608
	ds_read_b128 v[100:103], v35 offset:20224
	ds_read_b128 v[116:119], v35 offset:3840
	s_waitcnt lgkmcnt(5)
; __device__ __forceinline__ float allreduce16(float x) { x += dppf(x, 0); x += dppf(x, 1); x += dppf(x, 2); x += dppf(x, 3); return x; }
; __device__ void rw_scan(const Params& p, int l, unsigned char* shm, int item) {
;     ...
;                 for (int s2 = 0; s2 < 16; ++s2) {
;                     const int s = hs * 16 + s2, sn = (s + 1) & (TC - 1);
;                     const f32x4 na4 = *(const f32x4*)(sr + 3 * 2048 + sn * 64), nw4 = *(const f32x4*)(sr + 2048 + sn * 64), nb4 = *(const f32x4*)(sr + 4 * 2048 + sn * 64), nk4 = *(const f32x4*)(sr + 2 * 2048 + sn * 64), nr4 = *(const f32x4*)(sr + sn * 64);
;                     const float nvv = sv[sn * 16];
;                     f32x2 tq = S01 * (f32x2){a4[0], a4[1]}; tq = S23 * (f32x2){a4[2], a4[3]} + tq;
;                     const float sav = allreduce16(tq[0] + tq[1]);
;                     f32x2 u0 = (f32x2){b4[0], b4[1]} * sav, u1 = (f32x2){b4[2], b4[3]} * sav;
;                     u0 = (f32x2){k4[0], k4[1]} * vv + u0; u1 = (f32x2){k4[2], k4[3]} * vv + u1;
;                     S01 = S01 * (f32x2){w4[0], w4[1]} + u0; S23 = S23 * (f32x2){w4[2], w4[3]} + u1;
;                     f32x2 oq = S01 * (f32x2){r4[0], r4[1]}; oq = S23 * (f32x2){r4[2], r4[3]} + oq;
;                     pp[s2 * 64] = oq[0] + oq[1];
;                     a4 = na4; w4 = nw4; b4 = nb4; k4 = nk4; r4 = nr4; vv = nvv;
;                 }
;                 { const int s2 = lane >> 2, rr = lane & 3; const float* q_ = part + w * 1024 + s2 * 64 + rr * 16;
;                   const f32x4 x0 = *(const f32x4*)q_, x1 = *(const f32x4*)(q_ + 4), x2 = *(const f32x4*)(q_ + 8), x3 = *(const f32x4*)(q_ + 12);
;                   const float ov = ((x0[0] + x0[1]) + (x0[2] + x0[3])) + ((x1[0] + x1[1]) + (x1[2] + x1[3])) + ((x2[0] + x2[1]) + (x2[2] + x2[3])) + ((x3[0] + x3[1]) + (x3[2] + x3[3]));
;                   const int st2 = ck * TC + hs * 16 + s2; const int t2 = d ? (T - 1 - st2) : st2;
;                   yout[(size_t)(b * T + t2) * 768 + h * 64 + quarter * 16 + w * 4 + rr] = ov; }
	v_mul_f32_e32 v10, v2, v48
	v_mul_f32_e32 v6, v96, v122
	v_fmac_f32_e32 v10, v3, v49
	v_mul_f32_e32 v7, v97, v122
	v_fmac_f32_e32 v10, v4, v50
	v_mul_f32_e32 v8, v98, v122
	v_fmac_f32_e32 v10, v5, v51
	v_mul_f32_e32 v9, v99, v122
	v_fmac_f32_e32 v6, v2, v64
	v_add_f32_dpp v10, v10, v10 quad_perm:[1,0,3,2] row_mask:0xf bank_mask:0xf bound_ctrl:1
	v_fmac_f32_e32 v7, v3, v65
	v_fmac_f32_e32 v8, v4, v66
	v_add_f32_dpp v10, v10, v10 quad_perm:[2,3,0,1] row_mask:0xf bank_mask:0xf bound_ctrl:1
	v_fmac_f32_e32 v9, v5, v67
	v_mul_f32_e32 v13, v2, v108
	v_add_f32_dpp v10, v10, v10 row_half_mirror row_mask:0xf bank_mask:0xf bound_ctrl:1
	v_fmac_f32_e32 v13, v3, v109
	v_fmac_f32_e32 v13, v4, v110
	v_add_f32_dpp v10, v10, v10 row_mirror row_mask:0xf bank_mask:0xf bound_ctrl:1
	v_fmac_f32_e32 v6, v80, v10
	v_fmac_f32_e32 v7, v81, v10
	v_fmac_f32_e32 v8, v82, v10
	v_fmac_f32_e32 v9, v83, v10
	v_fmac_f32_e32 v13, v5, v111
	ds_write2st64_b32 v30, v12, v13 offset0:12 offset1:13
	ds_read_b128 v[40:43], v35 offset:28672
	ds_read_b128 v[56:59], v35 offset:12288
	ds_read_b128 v[72:75], v35 offset:36864
	ds_read_b128 v[88:91], v35 offset:20480
	ds_read_b128 v[104:107], v35 offset:4096
	ds_read2_b32 v[124:125], v38 offset0:0 offset1:16
	s_waitcnt lgkmcnt(7)
	v_mul_f32_e32 v11, v6, v52
	v_mul_f32_e32 v2, v100, v123
	v_fmac_f32_e32 v11, v7, v53
	v_mul_f32_e32 v3, v101, v123
	v_fmac_f32_e32 v11, v8, v54
	v_mul_f32_e32 v4, v102, v123
	v_fmac_f32_e32 v11, v9, v55
	v_mul_f32_e32 v5, v103, v123
	v_fmac_f32_e32 v2, v6, v68
	v_add_f32_dpp v11, v11, v11 quad_perm:[1,0,3,2] row_mask:0xf bank_mask:0xf bound_ctrl:1
	v_fmac_f32_e32 v3, v7, v69
	v_fmac_f32_e32 v4, v8, v70
	v_add_f32_dpp v11, v11, v11 quad_perm:[2,3,0,1] row_mask:0xf bank_mask:0xf bound_ctrl:1
	v_fmac_f32_e32 v5, v9, v71
	v_mul_f32_e32 v12, v6, v112
	v_add_f32_dpp v11, v11, v11 row_half_mirror row_mask:0xf bank_mask:0xf bound_ctrl:1
	v_fmac_f32_e32 v12, v7, v113
	v_fmac_f32_e32 v12, v8, v114
	v_add_f32_dpp v11, v11, v11 row_mirror row_mask:0xf bank_mask:0xf bound_ctrl:1
	v_fmac_f32_e32 v2, v84, v11
	v_fmac_f32_e32 v3, v85, v11
	v_fmac_f32_e32 v4, v86, v11
	v_fmac_f32_e32 v5, v87, v11
	v_fmac_f32_e32 v12, v9, v115
	ds_read_b128 v[44:47], v35 offset:28928
	ds_read_b128 v[60:63], v35 offset:12544
	ds_read_b128 v[76:79], v35 offset:37120
	ds_read_b128 v[92:95], v35 offset:20736
	ds_read_b128 v[108:111], v35 offset:4352
	s_waitcnt lgkmcnt(5)
	v_mul_f32_e32 v10, v2, v40
	v_mul_f32_e32 v6, v88, v124
	v_fmac_f32_e32 v10, v3, v41
	v_mul_f32_e32 v7, v89, v124
	v_fmac_f32_e32 v10, v4, v42
	v_mul_f32_e32 v8, v90, v124
	v_fmac_f32_e32 v10, v5, v43
	v_mul_f32_e32 v9, v91, v124
	v_fmac_f32_e32 v6, v2, v56
	v_add_f32_dpp v10, v10, v10 quad_perm:[1,0,3,2] row_mask:0xf bank_mask:0xf bound_ctrl:1
	v_fmac_f32_e32 v7, v3, v57
	v_fmac_f32_e32 v8, v4, v58
	v_add_f32_dpp v10, v10, v10 quad_perm:[2,3,0,1] row_mask:0xf bank_mask:0xf bound_ctrl:1
	v_fmac_f32_e32 v9, v5, v59
	v_mul_f32_e32 v13, v2, v116
	v_add_f32_dpp v10, v10, v10 row_half_mirror row_mask:0xf bank_mask:0xf bound_ctrl:1
	v_fmac_f32_e32 v13, v3, v117
	v_fmac_f32_e32 v13, v4, v118
	v_add_f32_dpp v10, v10, v10 row_mirror row_mask:0xf bank_mask:0xf bound_ctrl:1
	v_fmac_f32_e32 v6, v72, v10
	v_fmac_f32_e32 v7, v73, v10
	v_fmac_f32_e32 v8, v74, v10
	v_fmac_f32_e32 v9, v75, v10
	v_fmac_f32_e32 v13, v5, v119
	ds_write2st64_b32 v30, v12, v13 offset0:14 offset1:15
	ds_read_b128 v[142:145], v34
	ds_read_b128 v[146:149], v34 offset:16
	ds_read_b128 v[150:153], v34 offset:32
	ds_read_b128 v[154:157], v34 offset:48
	ds_read_b128 v[48:51], v35 offset:29184
	ds_read_b128 v[64:67], v35 offset:12800
	ds_read_b128 v[80:83], v35 offset:37376
	ds_read_b128 v[96:99], v35 offset:20992
	ds_read_b128 v[112:115], v35 offset:4608
	ds_read2_b32 v[120:121], v38 offset0:32 offset1:48
	v_add_u32_e32 v182, 16, v23
	v_cndmask_b32_e32 v182, v182, v32, vcc
	v_add_u32_e32 v182, s4, v182
	v_mad_i64_i32 v[180:181], s[6:7], v182, s10, v[24:25]
	s_waitcnt lgkmcnt(9)
	v_add_f32_e32 v158, v142, v143
	v_add_f32_e32 v159, v144, v145
	v_add_f32_e32 v158, v158, v159
	s_waitcnt lgkmcnt(8)
	v_add_f32_e32 v159, v146, v147
	v_add_f32_e32 v179, v148, v149
	v_add_f32_e32 v159, v159, v179
	v_add_f32_e32 v158, v158, v159
	s_waitcnt lgkmcnt(7)
	v_add_f32_e32 v159, v150, v151
	v_add_f32_e32 v179, v152, v153
	v_add_f32_e32 v159, v159, v179
	v_add_f32_e32 v158, v158, v159
	s_waitcnt lgkmcnt(6)
	v_add_f32_e32 v159, v154, v155
	v_add_f32_e32 v179, v156, v157
	v_add_f32_e32 v159, v159, v179
	v_add_f32_e32 v158, v158, v159
	global_store_dword v[180:181], v158, off
	s_waitcnt lgkmcnt(11)
	v_mul_f32_e32 v11, v6, v44
	v_mul_f32_e32 v2, v92, v125
	v_fmac_f32_e32 v11, v7, v45
	v_mul_f32_e32 v3, v93, v125
	v_fmac_f32_e32 v11, v8, v46
	v_mul_f32_e32 v4, v94, v125
	v_fmac_f32_e32 v11, v9, v47
	v_mul_f32_e32 v5, v95, v125
	v_fmac_f32_e32 v2, v6, v60
	v_add_f32_dpp v11, v11, v11 quad_perm:[1,0,3,2] row_mask:0xf bank_mask:0xf bound_ctrl:1
	v_fmac_f32_e32 v3, v7, v61
	v_fmac_f32_e32 v4, v8, v62
	v_add_f32_dpp v11, v11, v11 quad_perm:[2,3,0,1] row_mask:0xf bank_mask:0xf bound_ctrl:1
	v_fmac_f32_e32 v5, v9, v63
	v_mul_f32_e32 v12, v6, v104
	v_add_f32_dpp v11, v11, v11 row_half_mirror row_mask:0xf bank_mask:0xf bound_ctrl:1
	v_fmac_f32_e32 v12, v7, v105
	v_fmac_f32_e32 v12, v8, v106
	v_add_f32_dpp v11, v11, v11 row_mirror row_mask:0xf bank_mask:0xf bound_ctrl:1
	v_fmac_f32_e32 v2, v76, v11
	v_fmac_f32_e32 v3, v77, v11
	v_fmac_f32_e32 v4, v78, v11
	v_fmac_f32_e32 v5, v79, v11
	v_fmac_f32_e32 v12, v9, v107
	ds_read_b128 v[52:55], v35 offset:29440
	ds_read_b128 v[68:71], v35 offset:13056
	ds_read_b128 v[84:87], v35 offset:37632
	ds_read_b128 v[100:103], v35 offset:21248
	ds_read_b128 v[116:119], v35 offset:4864
	s_waitcnt lgkmcnt(5)
; __device__ __forceinline__ float allreduce16(float x) { x += dppf(x, 0); x += dppf(x, 1); x += dppf(x, 2); x += dppf(x, 3); return x; }
; __device__ void rw_scan(const Params& p, int l, unsigned char* shm, int item) {
;     ...
;                 for (int s2 = 0; s2 < 16; ++s2) {
;                     const int s = hs * 16 + s2, sn = (s + 1) & (TC - 1);
;                     const f32x4 na4 = *(const f32x4*)(sr + 3 * 2048 + sn * 64), nw4 = *(const f32x4*)(sr + 2048 + sn * 64), nb4 = *(const f32x4*)(sr + 4 * 2048 + sn * 64), nk4 = *(const f32x4*)(sr + 2 * 2048 + sn * 64), nr4 = *(const f32x4*)(sr + sn * 64);
;                     const float nvv = sv[sn * 16];
;                     f32x2 tq = S01 * (f32x2){a4[0], a4[1]}; tq = S23 * (f32x2){a4[2], a4[3]} + tq;
;                     const float sav = allreduce16(tq[0] + tq[1]);
;                     f32x2 u0 = (f32x2){b4[0], b4[1]} * sav, u1 = (f32x2){b4[2], b4[3]} * sav;
;                     u0 = (f32x2){k4[0], k4[1]} * vv + u0; u1 = (f32x2){k4[2], k4[3]} * vv + u1;
;                     S01 = S01 * (f32x2){w4[0], w4[1]} + u0; S23 = S23 * (f32x2){w4[2], w4[3]} + u1;
;                     f32x2 oq = S01 * (f32x2){r4[0], r4[1]}; oq = S23 * (f32x2){r4[2], r4[3]} + oq;
;                     pp[s2 * 64] = oq[0] + oq[1];
;                     a4 = na4; w4 = nw4; b4 = nb4; k4 = nk4; r4 = nr4; vv = nvv;
;                 }
	v_mul_f32_e32 v10, v2, v48
	v_mul_f32_e32 v6, v96, v120
	v_fmac_f32_e32 v10, v3, v49
	v_mul_f32_e32 v7, v97, v120
	v_fmac_f32_e32 v10, v4, v50
	v_mul_f32_e32 v8, v98, v120
	v_fmac_f32_e32 v10, v5, v51
	v_mul_f32_e32 v9, v99, v120
	v_fmac_f32_e32 v6, v2, v64
	v_add_f32_dpp v10, v10, v10 quad_perm:[1,0,3,2] row_mask:0xf bank_mask:0xf bound_ctrl:1
	v_fmac_f32_e32 v7, v3, v65
	v_fmac_f32_e32 v8, v4, v66
	v_add_f32_dpp v10, v10, v10 quad_perm:[2,3,0,1] row_mask:0xf bank_mask:0xf bound_ctrl:1
	v_fmac_f32_e32 v9, v5, v67
	v_mul_f32_e32 v13, v2, v108
	v_add_f32_dpp v10, v10, v10 row_half_mirror row_mask:0xf bank_mask:0xf bound_ctrl:1
	v_fmac_f32_e32 v13, v3, v109
	v_fmac_f32_e32 v13, v4, v110
	v_add_f32_dpp v10, v10, v10 row_mirror row_mask:0xf bank_mask:0xf bound_ctrl:1
	v_fmac_f32_e32 v6, v80, v10
	v_fmac_f32_e32 v7, v81, v10
	v_fmac_f32_e32 v8, v82, v10
	v_fmac_f32_e32 v9, v83, v10
	v_fmac_f32_e32 v13, v5, v111
	ds_write2st64_b32 v30, v12, v13 offset0:0 offset1:1
	ds_read_b128 v[40:43], v35 offset:29696
	ds_read_b128 v[56:59], v35 offset:13312
	ds_read_b128 v[72:75], v35 offset:37888
	ds_read_b128 v[88:91], v35 offset:21504
	ds_read_b128 v[104:107], v35 offset:5120
	ds_read2_b32 v[122:123], v38 offset0:64 offset1:80
	s_waitcnt lgkmcnt(7)
	v_mul_f32_e32 v11, v6, v52
	v_mul_f32_e32 v2, v100, v121
	v_fmac_f32_e32 v11, v7, v53
	v_mul_f32_e32 v3, v101, v121
	v_fmac_f32_e32 v11, v8, v54
	v_mul_f32_e32 v4, v102, v121
	v_fmac_f32_e32 v11, v9, v55
	v_mul_f32_e32 v5, v103, v121
	v_fmac_f32_e32 v2, v6, v68
	v_add_f32_dpp v11, v11, v11 quad_perm:[1,0,3,2] row_mask:0xf bank_mask:0xf bound_ctrl:1
	v_fmac_f32_e32 v3, v7, v69
	v_fmac_f32_e32 v4, v8, v70
	v_add_f32_dpp v11, v11, v11 quad_perm:[2,3,0,1] row_mask:0xf bank_mask:0xf bound_ctrl:1
	v_fmac_f32_e32 v5, v9, v71
	v_mul_f32_e32 v12, v6, v112
	v_add_f32_dpp v11, v11, v11 row_half_mirror row_mask:0xf bank_mask:0xf bound_ctrl:1
	v_fmac_f32_e32 v12, v7, v113
	v_fmac_f32_e32 v12, v8, v114
	v_add_f32_dpp v11, v11, v11 row_mirror row_mask:0xf bank_mask:0xf bound_ctrl:1
	v_fmac_f32_e32 v2, v84, v11
	v_fmac_f32_e32 v3, v85, v11
	v_fmac_f32_e32 v4, v86, v11
	v_fmac_f32_e32 v5, v87, v11
	v_fmac_f32_e32 v12, v9, v115
	ds_read_b128 v[44:47], v35 offset:29952
	ds_read_b128 v[60:63], v35 offset:13568
	ds_read_b128 v[76:79], v35 offset:38144
	ds_read_b128 v[92:95], v35 offset:21760
	ds_read_b128 v[108:111], v35 offset:5376
	s_waitcnt lgkmcnt(5)
	v_mul_f32_e32 v10, v2, v40
	v_mul_f32_e32 v6, v88, v122
	v_fmac_f32_e32 v10, v3, v41
	v_mul_f32_e32 v7, v89, v122
	v_fmac_f32_e32 v10, v4, v42
	v_mul_f32_e32 v8, v90, v122
	v_fmac_f32_e32 v10, v5, v43
	v_mul_f32_e32 v9, v91, v122
	v_fmac_f32_e32 v6, v2, v56
	v_add_f32_dpp v10, v10, v10 quad_perm:[1,0,3,2] row_mask:0xf bank_mask:0xf bound_ctrl:1
	v_fmac_f32_e32 v7, v3, v57
	v_fmac_f32_e32 v8, v4, v58
	v_add_f32_dpp v10, v10, v10 quad_perm:[2,3,0,1] row_mask:0xf bank_mask:0xf bound_ctrl:1
	v_fmac_f32_e32 v9, v5, v59
	v_mul_f32_e32 v13, v2, v116
	v_add_f32_dpp v10, v10, v10 row_half_mirror row_mask:0xf bank_mask:0xf bound_ctrl:1
	v_fmac_f32_e32 v13, v3, v117
	v_fmac_f32_e32 v13, v4, v118
	v_add_f32_dpp v10, v10, v10 row_mirror row_mask:0xf bank_mask:0xf bound_ctrl:1
	v_fmac_f32_e32 v6, v72, v10
	v_fmac_f32_e32 v7, v73, v10
	v_fmac_f32_e32 v8, v74, v10
	v_fmac_f32_e32 v9, v75, v10
	v_fmac_f32_e32 v13, v5, v119
	ds_write2st64_b32 v30, v12, v13 offset0:2 offset1:3
	ds_read_b128 v[48:51], v35 offset:30208
	ds_read_b128 v[64:67], v35 offset:13824
	ds_read_b128 v[80:83], v35 offset:38400
	ds_read_b128 v[96:99], v35 offset:22016
	ds_read_b128 v[112:115], v35 offset:5632
	ds_read2_b32 v[124:125], v38 offset0:96 offset1:112
	s_waitcnt lgkmcnt(7)
	v_mul_f32_e32 v11, v6, v44
	v_mul_f32_e32 v2, v92, v123
	v_fmac_f32_e32 v11, v7, v45
	v_mul_f32_e32 v3, v93, v123
	v_fmac_f32_e32 v11, v8, v46
	v_mul_f32_e32 v4, v94, v123
	v_fmac_f32_e32 v11, v9, v47
	v_mul_f32_e32 v5, v95, v123
	v_fmac_f32_e32 v2, v6, v60
	v_add_f32_dpp v11, v11, v11 quad_perm:[1,0,3,2] row_mask:0xf bank_mask:0xf bound_ctrl:1
	v_fmac_f32_e32 v3, v7, v61
	v_fmac_f32_e32 v4, v8, v62
	v_add_f32_dpp v11, v11, v11 quad_perm:[2,3,0,1] row_mask:0xf bank_mask:0xf bound_ctrl:1
	v_fmac_f32_e32 v5, v9, v63
	v_mul_f32_e32 v12, v6, v104
	v_add_f32_dpp v11, v11, v11 row_half_mirror row_mask:0xf bank_mask:0xf bound_ctrl:1
	v_fmac_f32_e32 v12, v7, v105
	v_fmac_f32_e32 v12, v8, v106
	v_add_f32_dpp v11, v11, v11 row_mirror row_mask:0xf bank_mask:0xf bound_ctrl:1
	v_fmac_f32_e32 v2, v76, v11
	v_fmac_f32_e32 v3, v77, v11
	v_fmac_f32_e32 v4, v78, v11
	v_fmac_f32_e32 v5, v79, v11
	v_fmac_f32_e32 v12, v9, v107
	ds_read_b128 v[52:55], v35 offset:30464
	ds_read_b128 v[68:71], v35 offset:14080
	ds_read_b128 v[84:87], v35 offset:38656
	ds_read_b128 v[100:103], v35 offset:22272
	ds_read_b128 v[116:119], v35 offset:5888
	s_waitcnt lgkmcnt(5)
	v_mul_f32_e32 v10, v2, v48
	v_mul_f32_e32 v6, v96, v124
	v_fmac_f32_e32 v10, v3, v49
	v_mul_f32_e32 v7, v97, v124
	v_fmac_f32_e32 v10, v4, v50
	v_mul_f32_e32 v8, v98, v124
	v_fmac_f32_e32 v10, v5, v51
	v_mul_f32_e32 v9, v99, v124
	v_fmac_f32_e32 v6, v2, v64
	v_add_f32_dpp v10, v10, v10 quad_perm:[1,0,3,2] row_mask:0xf bank_mask:0xf bound_ctrl:1
	v_fmac_f32_e32 v7, v3, v65
	v_fmac_f32_e32 v8, v4, v66
	v_add_f32_dpp v10, v10, v10 quad_perm:[2,3,0,1] row_mask:0xf bank_mask:0xf bound_ctrl:1
	v_fmac_f32_e32 v9, v5, v67
	v_mul_f32_e32 v13, v2, v108
	v_add_f32_dpp v10, v10, v10 row_half_mirror row_mask:0xf bank_mask:0xf bound_ctrl:1
	v_fmac_f32_e32 v13, v3, v109
	v_fmac_f32_e32 v13, v4, v110
	v_add_f32_dpp v10, v10, v10 row_mirror row_mask:0xf bank_mask:0xf bound_ctrl:1
	v_fmac_f32_e32 v6, v80, v10
	v_fmac_f32_e32 v7, v81, v10
	v_fmac_f32_e32 v8, v82, v10
	v_fmac_f32_e32 v9, v83, v10
	v_fmac_f32_e32 v13, v5, v111
	ds_write2st64_b32 v30, v12, v13 offset0:4 offset1:5
	ds_read_b128 v[40:43], v35 offset:30720
	ds_read_b128 v[56:59], v35 offset:14336
	ds_read_b128 v[72:75], v35 offset:38912
	ds_read_b128 v[88:91], v35 offset:22528
	ds_read_b128 v[104:107], v35 offset:6144
	ds_read2_b32 v[120:121], v38 offset0:128 offset1:144
	s_waitcnt lgkmcnt(7)
; __device__ __forceinline__ float allreduce16(float x) { x += dppf(x, 0); x += dppf(x, 1); x += dppf(x, 2); x += dppf(x, 3); return x; }
; __device__ void rw_scan(const Params& p, int l, unsigned char* shm, int item) {
;     ...
;                 for (int s2 = 0; s2 < 16; ++s2) {
;                     const int s = hs * 16 + s2, sn = (s + 1) & (TC - 1);
;                     const f32x4 na4 = *(const f32x4*)(sr + 3 * 2048 + sn * 64), nw4 = *(const f32x4*)(sr + 2048 + sn * 64), nb4 = *(const f32x4*)(sr + 4 * 2048 + sn * 64), nk4 = *(const f32x4*)(sr + 2 * 2048 + sn * 64), nr4 = *(const f32x4*)(sr + sn * 64);
;                     const float nvv = sv[sn * 16];
;                     f32x2 tq = S01 * (f32x2){a4[0], a4[1]}; tq = S23 * (f32x2){a4[2], a4[3]} + tq;
;                     const float sav = allreduce16(tq[0] + tq[1]);
;                     f32x2 u0 = (f32x2){b4[0], b4[1]} * sav, u1 = (f32x2){b4[2], b4[3]} * sav;
;                     u0 = (f32x2){k4[0], k4[1]} * vv + u0; u1 = (f32x2){k4[2], k4[3]} * vv + u1;
;                     S01 = S01 * (f32x2){w4[0], w4[1]} + u0; S23 = S23 * (f32x2){w4[2], w4[3]} + u1;
;                     f32x2 oq = S01 * (f32x2){r4[0], r4[1]}; oq = S23 * (f32x2){r4[2], r4[3]} + oq;
;                     pp[s2 * 64] = oq[0] + oq[1];
;                     a4 = na4; w4 = nw4; b4 = nb4; k4 = nk4; r4 = nr4; vv = nvv;
;                 }
	v_mul_f32_e32 v11, v6, v52
	v_mul_f32_e32 v2, v100, v125
	v_fmac_f32_e32 v11, v7, v53
	v_mul_f32_e32 v3, v101, v125
	v_fmac_f32_e32 v11, v8, v54
	v_mul_f32_e32 v4, v102, v125
	v_fmac_f32_e32 v11, v9, v55
	v_mul_f32_e32 v5, v103, v125
	v_fmac_f32_e32 v2, v6, v68
	v_add_f32_dpp v11, v11, v11 quad_perm:[1,0,3,2] row_mask:0xf bank_mask:0xf bound_ctrl:1
	v_fmac_f32_e32 v3, v7, v69
	v_fmac_f32_e32 v4, v8, v70
	v_add_f32_dpp v11, v11, v11 quad_perm:[2,3,0,1] row_mask:0xf bank_mask:0xf bound_ctrl:1
	v_fmac_f32_e32 v5, v9, v71
	v_mul_f32_e32 v12, v6, v112
	v_add_f32_dpp v11, v11, v11 row_half_mirror row_mask:0xf bank_mask:0xf bound_ctrl:1
	v_fmac_f32_e32 v12, v7, v113
	v_fmac_f32_e32 v12, v8, v114
	v_add_f32_dpp v11, v11, v11 row_mirror row_mask:0xf bank_mask:0xf bound_ctrl:1
	v_fmac_f32_e32 v2, v84, v11
	v_fmac_f32_e32 v3, v85, v11
	v_fmac_f32_e32 v4, v86, v11
	v_fmac_f32_e32 v5, v87, v11
	v_fmac_f32_e32 v12, v9, v115
	ds_read_b128 v[44:47], v35 offset:30976
	ds_read_b128 v[60:63], v35 offset:14592
	ds_read_b128 v[76:79], v35 offset:39168
	ds_read_b128 v[92:95], v35 offset:22784
	ds_read_b128 v[108:111], v35 offset:6400
	s_waitcnt lgkmcnt(5)
	v_mul_f32_e32 v10, v2, v40
	v_mul_f32_e32 v6, v88, v120
	v_fmac_f32_e32 v10, v3, v41
	v_mul_f32_e32 v7, v89, v120
	v_fmac_f32_e32 v10, v4, v42
	v_mul_f32_e32 v8, v90, v120
	v_fmac_f32_e32 v10, v5, v43
	v_mul_f32_e32 v9, v91, v120
	v_fmac_f32_e32 v6, v2, v56
	v_add_f32_dpp v10, v10, v10 quad_perm:[1,0,3,2] row_mask:0xf bank_mask:0xf bound_ctrl:1
	v_fmac_f32_e32 v7, v3, v57
	v_fmac_f32_e32 v8, v4, v58
	v_add_f32_dpp v10, v10, v10 quad_perm:[2,3,0,1] row_mask:0xf bank_mask:0xf bound_ctrl:1
	v_fmac_f32_e32 v9, v5, v59
	v_mul_f32_e32 v13, v2, v116
	v_add_f32_dpp v10, v10, v10 row_half_mirror row_mask:0xf bank_mask:0xf bound_ctrl:1
	v_fmac_f32_e32 v13, v3, v117
	v_fmac_f32_e32 v13, v4, v118
	v_add_f32_dpp v10, v10, v10 row_mirror row_mask:0xf bank_mask:0xf bound_ctrl:1
	v_fmac_f32_e32 v6, v72, v10
	v_fmac_f32_e32 v7, v73, v10
	v_fmac_f32_e32 v8, v74, v10
	v_fmac_f32_e32 v9, v75, v10
	v_fmac_f32_e32 v13, v5, v119
	ds_write2st64_b32 v30, v12, v13 offset0:6 offset1:7
	ds_read_b128 v[48:51], v35 offset:31232
	ds_read_b128 v[64:67], v35 offset:14848
	ds_read_b128 v[80:83], v35 offset:39424
	ds_read_b128 v[96:99], v35 offset:23040
	ds_read_b128 v[112:115], v35 offset:6656
	ds_read2_b32 v[122:123], v38 offset0:160 offset1:176
	s_waitcnt lgkmcnt(7)
	v_mul_f32_e32 v11, v6, v44
	v_mul_f32_e32 v2, v92, v121
	v_fmac_f32_e32 v11, v7, v45
	v_mul_f32_e32 v3, v93, v121
	v_fmac_f32_e32 v11, v8, v46
	v_mul_f32_e32 v4, v94, v121
	v_fmac_f32_e32 v11, v9, v47
	v_mul_f32_e32 v5, v95, v121
	v_fmac_f32_e32 v2, v6, v60
	v_add_f32_dpp v11, v11, v11 quad_perm:[1,0,3,2] row_mask:0xf bank_mask:0xf bound_ctrl:1
	v_fmac_f32_e32 v3, v7, v61
	v_fmac_f32_e32 v4, v8, v62
	v_add_f32_dpp v11, v11, v11 quad_perm:[2,3,0,1] row_mask:0xf bank_mask:0xf bound_ctrl:1
	v_fmac_f32_e32 v5, v9, v63
	v_mul_f32_e32 v12, v6, v104
	v_add_f32_dpp v11, v11, v11 row_half_mirror row_mask:0xf bank_mask:0xf bound_ctrl:1
	v_fmac_f32_e32 v12, v7, v105
	v_fmac_f32_e32 v12, v8, v106
	v_add_f32_dpp v11, v11, v11 row_mirror row_mask:0xf bank_mask:0xf bound_ctrl:1
	v_fmac_f32_e32 v2, v76, v11
	v_fmac_f32_e32 v3, v77, v11
	v_fmac_f32_e32 v4, v78, v11
	v_fmac_f32_e32 v5, v79, v11
	v_fmac_f32_e32 v12, v9, v107
	ds_read_b128 v[52:55], v35 offset:31488
	ds_read_b128 v[68:71], v35 offset:15104
	ds_read_b128 v[84:87], v35 offset:39680
	ds_read_b128 v[100:103], v35 offset:23296
	ds_read_b128 v[116:119], v35 offset:6912
	s_waitcnt lgkmcnt(5)
	v_mul_f32_e32 v10, v2, v48
	v_mul_f32_e32 v6, v96, v122
	v_fmac_f32_e32 v10, v3, v49
	v_mul_f32_e32 v7, v97, v122
	v_fmac_f32_e32 v10, v4, v50
	v_mul_f32_e32 v8, v98, v122
	v_fmac_f32_e32 v10, v5, v51
	v_mul_f32_e32 v9, v99, v122
	v_fmac_f32_e32 v6, v2, v64
	v_add_f32_dpp v10, v10, v10 quad_perm:[1,0,3,2] row_mask:0xf bank_mask:0xf bound_ctrl:1
	v_fmac_f32_e32 v7, v3, v65
	v_fmac_f32_e32 v8, v4, v66
	v_add_f32_dpp v10, v10, v10 quad_perm:[2,3,0,1] row_mask:0xf bank_mask:0xf bound_ctrl:1
	v_fmac_f32_e32 v9, v5, v67
	v_mul_f32_e32 v13, v2, v108
	v_add_f32_dpp v10, v10, v10 row_half_mirror row_mask:0xf bank_mask:0xf bound_ctrl:1
	v_fmac_f32_e32 v13, v3, v109
	v_fmac_f32_e32 v13, v4, v110
	v_add_f32_dpp v10, v10, v10 row_mirror row_mask:0xf bank_mask:0xf bound_ctrl:1
	v_fmac_f32_e32 v6, v80, v10
	v_fmac_f32_e32 v7, v81, v10
	v_fmac_f32_e32 v8, v82, v10
	v_fmac_f32_e32 v9, v83, v10
	v_fmac_f32_e32 v13, v5, v111
	ds_write2st64_b32 v30, v12, v13 offset0:8 offset1:9
	ds_read_b128 v[40:43], v35 offset:31744
	ds_read_b128 v[56:59], v35 offset:15360
	ds_read_b128 v[72:75], v35 offset:39936
	ds_read_b128 v[88:91], v35 offset:23552
	ds_read_b128 v[104:107], v35 offset:7168
	ds_read2_b32 v[124:125], v38 offset0:192 offset1:208
	s_waitcnt lgkmcnt(7)
	v_mul_f32_e32 v11, v6, v52
	v_mul_f32_e32 v2, v100, v123
	v_fmac_f32_e32 v11, v7, v53
	v_mul_f32_e32 v3, v101, v123
	v_fmac_f32_e32 v11, v8, v54
	v_mul_f32_e32 v4, v102, v123
	v_fmac_f32_e32 v11, v9, v55
	v_mul_f32_e32 v5, v103, v123
	v_fmac_f32_e32 v2, v6, v68
	v_add_f32_dpp v11, v11, v11 quad_perm:[1,0,3,2] row_mask:0xf bank_mask:0xf bound_ctrl:1
	v_fmac_f32_e32 v3, v7, v69
	v_fmac_f32_e32 v4, v8, v70
	v_add_f32_dpp v11, v11, v11 quad_perm:[2,3,0,1] row_mask:0xf bank_mask:0xf bound_ctrl:1
	v_fmac_f32_e32 v5, v9, v71
	v_mul_f32_e32 v12, v6, v112
	v_add_f32_dpp v11, v11, v11 row_half_mirror row_mask:0xf bank_mask:0xf bound_ctrl:1
	v_fmac_f32_e32 v12, v7, v113
	v_fmac_f32_e32 v12, v8, v114
	v_add_f32_dpp v11, v11, v11 row_mirror row_mask:0xf bank_mask:0xf bound_ctrl:1
	v_fmac_f32_e32 v2, v84, v11
	v_fmac_f32_e32 v3, v85, v11
	v_fmac_f32_e32 v4, v86, v11
	v_fmac_f32_e32 v5, v87, v11
	v_fmac_f32_e32 v12, v9, v115
	ds_read_b128 v[44:47], v35 offset:32000
	ds_read_b128 v[60:63], v35 offset:15616
	ds_read_b128 v[76:79], v35 offset:40192
	ds_read_b128 v[92:95], v35 offset:23808
	ds_read_b128 v[108:111], v35 offset:7424
	s_waitcnt lgkmcnt(5)
; __device__ __forceinline__ float allreduce16(float x) { x += dppf(x, 0); x += dppf(x, 1); x += dppf(x, 2); x += dppf(x, 3); return x; }
; __device__ void rw_scan(const Params& p, int l, unsigned char* shm, int item) {
;     ...
;                 for (int s2 = 0; s2 < 16; ++s2) {
;                     const int s = hs * 16 + s2, sn = (s + 1) & (TC - 1);
;                     const f32x4 na4 = *(const f32x4*)(sr + 3 * 2048 + sn * 64), nw4 = *(const f32x4*)(sr + 2048 + sn * 64), nb4 = *(const f32x4*)(sr + 4 * 2048 + sn * 64), nk4 = *(const f32x4*)(sr + 2 * 2048 + sn * 64), nr4 = *(const f32x4*)(sr + sn * 64);
;                     const float nvv = sv[sn * 16];
;                     f32x2 tq = S01 * (f32x2){a4[0], a4[1]}; tq = S23 * (f32x2){a4[2], a4[3]} + tq;
;                     const float sav = allreduce16(tq[0] + tq[1]);
;                     f32x2 u0 = (f32x2){b4[0], b4[1]} * sav, u1 = (f32x2){b4[2], b4[3]} * sav;
;                     u0 = (f32x2){k4[0], k4[1]} * vv + u0; u1 = (f32x2){k4[2], k4[3]} * vv + u1;
;                     S01 = S01 * (f32x2){w4[0], w4[1]} + u0; S23 = S23 * (f32x2){w4[2], w4[3]} + u1;
;                     f32x2 oq = S01 * (f32x2){r4[0], r4[1]}; oq = S23 * (f32x2){r4[2], r4[3]} + oq;
;                     pp[s2 * 64] = oq[0] + oq[1];
;                     a4 = na4; w4 = nw4; b4 = nb4; k4 = nk4; r4 = nr4; vv = nvv;
;                 }
;                 { const int s2 = lane >> 2, rr = lane & 3; const float* q_ = part + w * 1024 + s2 * 64 + rr * 16;
;                   const f32x4 x0 = *(const f32x4*)q_, x1 = *(const f32x4*)(q_ + 4), x2 = *(const f32x4*)(q_ + 8), x3 = *(const f32x4*)(q_ + 12);
;                   const float ov = ((x0[0] + x0[1]) + (x0[2] + x0[3])) + ((x1[0] + x1[1]) + (x1[2] + x1[3])) + ((x2[0] + x2[1]) + (x2[2] + x2[3])) + ((x3[0] + x3[1]) + (x3[2] + x3[3]));
;                   const int st2 = ck * TC + hs * 16 + s2; const int t2 = d ? (T - 1 - st2) : st2;
;                   yout[(size_t)(b * T + t2) * 768 + h * 64 + quarter * 16 + w * 4 + rr] = ov; }
;             }
;             __syncthreads();
;         }
	v_mul_f32_e32 v10, v2, v40
	v_mul_f32_e32 v6, v88, v124
	v_fmac_f32_e32 v10, v3, v41
	v_mul_f32_e32 v7, v89, v124
	v_fmac_f32_e32 v10, v4, v42
	v_mul_f32_e32 v8, v90, v124
	v_fmac_f32_e32 v10, v5, v43
	v_mul_f32_e32 v9, v91, v124
	v_fmac_f32_e32 v6, v2, v56
	v_add_f32_dpp v10, v10, v10 quad_perm:[1,0,3,2] row_mask:0xf bank_mask:0xf bound_ctrl:1
	v_fmac_f32_e32 v7, v3, v57
	v_fmac_f32_e32 v8, v4, v58
	v_add_f32_dpp v10, v10, v10 quad_perm:[2,3,0,1] row_mask:0xf bank_mask:0xf bound_ctrl:1
	v_fmac_f32_e32 v9, v5, v59
	v_mul_f32_e32 v13, v2, v116
	v_add_f32_dpp v10, v10, v10 row_half_mirror row_mask:0xf bank_mask:0xf bound_ctrl:1
	v_fmac_f32_e32 v13, v3, v117
	v_fmac_f32_e32 v13, v4, v118
	v_add_f32_dpp v10, v10, v10 row_mirror row_mask:0xf bank_mask:0xf bound_ctrl:1
	v_fmac_f32_e32 v6, v72, v10
	v_fmac_f32_e32 v7, v73, v10
	v_fmac_f32_e32 v8, v74, v10
	v_fmac_f32_e32 v9, v75, v10
	v_fmac_f32_e32 v13, v5, v119
	ds_write2st64_b32 v30, v12, v13 offset0:10 offset1:11
	ds_read_b128 v[48:51], v35 offset:32256
	ds_read_b128 v[64:67], v35 offset:15872
	ds_read_b128 v[80:83], v35 offset:40448
	ds_read_b128 v[96:99], v35 offset:24064
	ds_read_b128 v[112:115], v35 offset:7680
	ds_read2_b32 v[120:121], v38 offset0:224 offset1:240
	s_waitcnt lgkmcnt(7)
	v_mul_f32_e32 v11, v6, v44
	v_mul_f32_e32 v2, v92, v125
	v_fmac_f32_e32 v11, v7, v45
	v_mul_f32_e32 v3, v93, v125
	v_fmac_f32_e32 v11, v8, v46
	v_mul_f32_e32 v4, v94, v125
	v_fmac_f32_e32 v11, v9, v47
	v_mul_f32_e32 v5, v95, v125
	v_fmac_f32_e32 v2, v6, v60
	v_add_f32_dpp v11, v11, v11 quad_perm:[1,0,3,2] row_mask:0xf bank_mask:0xf bound_ctrl:1
	v_fmac_f32_e32 v3, v7, v61
	v_fmac_f32_e32 v4, v8, v62
	v_add_f32_dpp v11, v11, v11 quad_perm:[2,3,0,1] row_mask:0xf bank_mask:0xf bound_ctrl:1
	v_fmac_f32_e32 v5, v9, v63
	v_mul_f32_e32 v12, v6, v104
	v_add_f32_dpp v11, v11, v11 row_half_mirror row_mask:0xf bank_mask:0xf bound_ctrl:1
	v_fmac_f32_e32 v12, v7, v105
	v_fmac_f32_e32 v12, v8, v106
	v_add_f32_dpp v11, v11, v11 row_mirror row_mask:0xf bank_mask:0xf bound_ctrl:1
	v_fmac_f32_e32 v2, v76, v11
	v_fmac_f32_e32 v3, v77, v11
	v_fmac_f32_e32 v4, v78, v11
	v_fmac_f32_e32 v5, v79, v11
	v_fmac_f32_e32 v12, v9, v107
	ds_read_b128 v[52:55], v35 offset:32512
	ds_read_b128 v[68:71], v35 offset:16128
	ds_read_b128 v[84:87], v35 offset:40704
	ds_read_b128 v[100:103], v35 offset:24320
	ds_read_b128 v[116:119], v35 offset:7936
	s_waitcnt lgkmcnt(5)
	v_mul_f32_e32 v10, v2, v48
	v_mul_f32_e32 v6, v96, v120
	v_fmac_f32_e32 v10, v3, v49
	v_mul_f32_e32 v7, v97, v120
	v_fmac_f32_e32 v10, v4, v50
	v_mul_f32_e32 v8, v98, v120
	v_fmac_f32_e32 v10, v5, v51
	v_mul_f32_e32 v9, v99, v120
	v_fmac_f32_e32 v6, v2, v64
	v_add_f32_dpp v10, v10, v10 quad_perm:[1,0,3,2] row_mask:0xf bank_mask:0xf bound_ctrl:1
	v_fmac_f32_e32 v7, v3, v65
	v_fmac_f32_e32 v8, v4, v66
	v_add_f32_dpp v10, v10, v10 quad_perm:[2,3,0,1] row_mask:0xf bank_mask:0xf bound_ctrl:1
	v_fmac_f32_e32 v9, v5, v67
	v_mul_f32_e32 v13, v2, v108
	v_add_f32_dpp v10, v10, v10 row_half_mirror row_mask:0xf bank_mask:0xf bound_ctrl:1
	v_fmac_f32_e32 v13, v3, v109
	v_fmac_f32_e32 v13, v4, v110
	v_add_f32_dpp v10, v10, v10 row_mirror row_mask:0xf bank_mask:0xf bound_ctrl:1
	v_fmac_f32_e32 v6, v80, v10
	v_fmac_f32_e32 v7, v81, v10
	v_fmac_f32_e32 v8, v82, v10
	v_fmac_f32_e32 v9, v83, v10
	v_fmac_f32_e32 v13, v5, v111
	ds_write2st64_b32 v30, v12, v13 offset0:12 offset1:13
	s_waitcnt lgkmcnt(1)
	v_mul_f32_e32 v11, v6, v52
	v_mul_f32_e32 v2, v100, v121
	v_fmac_f32_e32 v11, v7, v53
	v_mul_f32_e32 v3, v101, v121
	v_fmac_f32_e32 v11, v8, v54
	v_mul_f32_e32 v4, v102, v121
	v_fmac_f32_e32 v11, v9, v55
	v_mul_f32_e32 v5, v103, v121
	v_fmac_f32_e32 v2, v6, v68
	v_add_f32_dpp v11, v11, v11 quad_perm:[1,0,3,2] row_mask:0xf bank_mask:0xf bound_ctrl:1
	v_fmac_f32_e32 v3, v7, v69
	v_fmac_f32_e32 v4, v8, v70
	v_add_f32_dpp v11, v11, v11 quad_perm:[2,3,0,1] row_mask:0xf bank_mask:0xf bound_ctrl:1
	v_fmac_f32_e32 v5, v9, v71
	v_mul_f32_e32 v12, v6, v112
	v_add_f32_dpp v11, v11, v11 row_half_mirror row_mask:0xf bank_mask:0xf bound_ctrl:1
	v_fmac_f32_e32 v12, v7, v113
	v_fmac_f32_e32 v12, v8, v114
	v_add_f32_dpp v11, v11, v11 row_mirror row_mask:0xf bank_mask:0xf bound_ctrl:1
	v_fmac_f32_e32 v2, v84, v11
	v_fmac_f32_e32 v3, v85, v11
	v_fmac_f32_e32 v4, v86, v11
	v_fmac_f32_e32 v5, v87, v11
	v_fmac_f32_e32 v12, v9, v115
	v_mul_f32_e32 v13, v2, v116
	s_add_i32 s3, s3, 1
	v_fmac_f32_e32 v13, v3, v117
	s_cmpk_eq_i32 s3, 0x200
	v_fmac_f32_e32 v13, v4, v118
	v_fmac_f32_e32 v13, v5, v119
	ds_write2st64_b32 v30, v12, v13 offset0:14 offset1:15
	ds_read_b128 v[142:145], v34
	ds_read_b128 v[146:149], v34 offset:16
	ds_read_b128 v[150:153], v34 offset:32
	ds_read_b128 v[154:157], v34 offset:48
	v_add_u32_e32 v182, 16, v32
	v_cndmask_b32_e32 v182, v23, v182, vcc
	v_add_u32_e32 v182, s4, v182
	v_mad_i64_i32 v[180:181], s[6:7], v182, s10, v[24:25]
	s_waitcnt lgkmcnt(3)
	v_add_f32_e32 v158, v142, v143
	v_add_f32_e32 v159, v144, v145
	v_add_f32_e32 v158, v158, v159
	s_waitcnt lgkmcnt(2)
	v_add_f32_e32 v159, v146, v147
	v_add_f32_e32 v179, v148, v149
	v_add_f32_e32 v159, v159, v179
	v_add_f32_e32 v158, v158, v159
	s_waitcnt lgkmcnt(1)
	v_add_f32_e32 v159, v150, v151
	v_add_f32_e32 v179, v152, v153
	v_add_f32_e32 v159, v159, v179
	v_add_f32_e32 v158, v158, v159
	s_waitcnt lgkmcnt(0)
	v_add_f32_e32 v159, v154, v155
	v_add_f32_e32 v179, v156, v157
	v_add_f32_e32 v159, v159, v179
	v_add_f32_e32 v158, v158, v159
	global_store_dword v[180:181], v158, off
	v_add_u32_e32 v32, 32, v32
	v_subrev_u32_e32 v23, 32, v23
	s_waitcnt lgkmcnt(0)
	s_barrier
	s_cbranch_scc0 .LBB0_304
	s_setprio 0
